# ph3 LoRA GEMM: column tiles pn>=4 start at K-tile 2 and run 2 of 3 loop iterations (their first two K-tiles of the block-diagonal weight are zero); exact
# baseline (speedup 1.0000x reference)
.LBB0_475:
	s_andn2_b64 vcc, exec, s[0:1]
	s_cbranch_vccnz .LBB0_567
	v_lshrrev_b32_e32 v3, 1, v210
	v_and_b32_e32 v10, 24, v3
	v_lshrrev_b32_e32 v3, 5, v210
	v_and_b32_e32 v3, 4, v3
	v_bfe_u32 v4, v210, 2, 2
	v_lshlrev_b32_e32 v0, 4, v210
	v_and_b32_e32 v1, 32, v210
	v_bfe_u32 v2, v210, 2, 4
	v_or3_b32 v3, v3, v4, v10
	v_lshrrev_b32_e32 v4, 3, v210
	s_movk_i32 s0, 0x70
	v_bitop3_b32 v8, v0, v1, 48 bitop3:0x6c
	v_and_or_b32 v5, v4, s0, v2
	s_movk_i32 s0, 0x60
	v_add_u32_e32 v0, 0x2000, v0
	v_and_or_b32 v4, v4, s0, v3
	v_lshrrev_b32_e32 v0, 7, v0
	s_movk_i32 s0, 0xf0
	v_and_or_b32 v2, v0, s0, v2
	s_movk_i32 s0, 0xe0
	s_lshr_b32 s1, s2, 6
	v_and_or_b32 v0, v0, s0, v3
	s_lshr_b32 s0, s2, 8
	s_lshl_b32 s11, s1, 10
	v_and_b32_e32 v9, 64, v210
	s_add_u32 s14, s72, 0xc80000
	v_or_b32_e32 v1, v8, v9
	s_addc_u32 s15, s73, 0
	s_mul_i32 s13, s48, 0x30000
	v_lshrrev_b32_e32 v1, 1, v1
	v_mul_u32_u24_e32 v4, 0x180, v4
	s_mul_hi_i32 s12, s48, 0x30000
	s_add_u32 s28, s14, s13
	v_or_b32_e32 v4, v4, v1
	s_addc_u32 s29, s15, s12
	s_cmp_gt_i32 s48, 3
	s_cselect_b32 s98, 0x100, 0
	s_add_u32 s28, s28, s98
	s_addc_u32 s29, s29, 0
	s_add_i32 s35, s11, 0
	v_lshlrev_b32_e32 v146, 1, v4
	v_mul_u32_u24_e32 v0, 0x180, v0
	s_add_i32 m0, s35, 0x10000
	v_or_b32_e32 v0, v0, v1
	global_load_lds_dwordx4 v146, s[28:29]
	s_add_i32 m0, s35, 0x12000
	v_lshlrev_b32_e32 v150, 1, v0
	s_add_u32 s12, s28, 0x18000
	global_load_lds_dwordx4 v150, s[28:29]
	s_addc_u32 s13, s29, 0
	s_add_i32 m0, s35, 0x14000
	s_mul_i32 s9, s8, 0x30000
	global_load_lds_dwordx4 v146, s[12:13]
	s_add_i32 m0, s35, 0x16000
	v_mul_u32_u24_e32 v11, 0x180, v5
	s_mul_hi_i32 s3, s8, 0x30000
	s_add_u32 s38, s40, s9
	v_or_b32_e32 v5, v1, v11
	v_mul_u32_u24_e32 v12, 0x180, v2
	s_addc_u32 s39, s41, s3
	s_cmp_gt_i32 s48, 3
	s_cselect_b32 s98, 0x100, 0
	s_add_u32 s38, s38, s98
	s_addc_u32 s39, s39, 0
	s_add_i32 s54, s35, 0x2000
	v_lshlrev_b32_e32 v144, 1, v5
	v_or_b32_e32 v2, v12, v1
	global_load_lds_dwordx4 v150, s[12:13]
	s_mov_b32 m0, s35
	s_add_u32 s12, s38, 0x18000
	v_lshlrev_b32_e32 v148, 1, v2
	global_load_lds_dwordx4 v144, s[38:39]
	s_mov_b32 m0, s54
	s_addc_u32 s13, s39, 0
	s_add_i32 s55, s35, 0x4000
	global_load_lds_dwordx4 v148, s[38:39]
	s_mov_b32 m0, s55
	s_add_i32 s56, s35, 0x6000
	global_load_lds_dwordx4 v144, s[12:13]
	s_mov_b32 m0, s56
	v_mov_b32_e32 v153, 0
	global_load_lds_dwordx4 v148, s[12:13]
	v_mov_b32_e32 v147, v153
	v_mov_b32_e32 v151, v153
	v_mov_b32_e32 v145, v153
	v_mov_b32_e32 v149, v153
	s_cmp_eq_u32 s0, 1
	s_mov_b32 s9, 0
	v_lshl_add_u64 v[6:7], s[28:29], 0, v[146:147]
	v_lshl_add_u64 v[4:5], s[28:29], 0, v[150:151]
	v_lshl_add_u64 v[0:1], s[38:39], 0, v[144:145]
	s_cselect_b64 s[12:13], -1, 0
	s_cmp_lg_u32 s0, 1
	v_lshl_add_u64 v[2:3], s[38:39], 0, v[148:149]
	s_cbranch_scc1 .LBB0_478
	s_barrier

.LBB0_483:
	s_nop 0
	v_cndmask_b32_e64 v0, 0, 1, s[2:3]
	v_cmp_ne_u32_e64 s[0:1], 1, v0
	s_andn2_b64 vcc, exec, s[2:3]
	s_mov_b64 s[20:21], s[38:39]
	s_cbranch_vccnz .LBB0_485
	s_mul_i32 s3, s67, 0x30000
	s_mul_hi_i32 s2, s67, 0x30000
	s_add_u32 s20, s40, s3
	s_addc_u32 s21, s41, s2
	s_cmp_gt_i32 s66, 3
	s_cselect_b32 s98, 0x100, 0
	s_add_u32 s20, s20, s98
	s_addc_u32 s21, s21, 0
.LBB0_485:
	s_and_b64 vcc, exec, s[0:1]
	s_mov_b64 s[22:23], s[28:29]
	s_cbranch_vccnz .LBB0_487
	s_mul_i32 s3, s66, 0x30000
	s_mul_hi_i32 s2, s66, 0x30000
	s_add_u32 s22, s14, s3
	s_addc_u32 s23, s15, s2
	s_cmp_gt_i32 s66, 3
	s_cselect_b32 s98, 0x100, 0
	s_add_u32 s22, s22, s98
	s_addc_u32 s23, s23, 0
.LBB0_487:
	s_add_u32 s2, s38, 0x18080
	s_addc_u32 s3, s39, 0
	s_add_u32 s49, s28, 0x100
	v_mov_b32_e32 v0, 0
	s_addc_u32 s52, s29, 0
	s_cmp_lt_i32 s48, 4
	s_cselect_b32 s53, 2, 0
	v_mov_b32_e32 v1, v0
	v_mov_b32_e32 v2, v0
	v_mov_b32_e32 v3, v0
	v_mov_b32_e32 v4, v0
	v_mov_b32_e32 v5, v0
	v_mov_b32_e32 v6, v0
	v_mov_b32_e32 v7, v0
	v_mov_b32_e32 v16, v0
	v_mov_b32_e32 v17, v0
	v_mov_b32_e32 v18, v0
	v_mov_b32_e32 v19, v0
	v_mov_b32_e32 v20, v0
	v_mov_b32_e32 v21, v0
	v_mov_b32_e32 v22, v0
	v_mov_b32_e32 v23, v0
	v_mov_b32_e32 v32, v0
	v_mov_b32_e32 v33, v0
	v_mov_b32_e32 v34, v0
	v_mov_b32_e32 v35, v0
	v_mov_b32_e32 v36, v0
	v_mov_b32_e32 v37, v0
	v_mov_b32_e32 v38, v0
	v_mov_b32_e32 v39, v0
	v_mov_b32_e32 v48, v0
	v_mov_b32_e32 v49, v0
	v_mov_b32_e32 v50, v0
	v_mov_b32_e32 v51, v0
	v_mov_b32_e32 v52, v0
	v_mov_b32_e32 v53, v0
	v_mov_b32_e32 v54, v0
	v_mov_b32_e32 v55, v0
	v_mov_b32_e32 v8, v0
	v_mov_b32_e32 v9, v0
	v_mov_b32_e32 v10, v0
	v_mov_b32_e32 v11, v0
	v_mov_b32_e32 v12, v0
	v_mov_b32_e32 v13, v0
	v_mov_b32_e32 v14, v0
	v_mov_b32_e32 v15, v0
	v_mov_b32_e32 v24, v0
	v_mov_b32_e32 v25, v0
	v_mov_b32_e32 v26, v0
	v_mov_b32_e32 v27, v0
	v_mov_b32_e32 v28, v0
	v_mov_b32_e32 v29, v0
	v_mov_b32_e32 v30, v0
	v_mov_b32_e32 v31, v0
	v_mov_b32_e32 v40, v0
	v_mov_b32_e32 v41, v0
	v_mov_b32_e32 v42, v0
	v_mov_b32_e32 v43, v0
	v_mov_b32_e32 v44, v0
	v_mov_b32_e32 v45, v0
	v_mov_b32_e32 v46, v0
	v_mov_b32_e32 v47, v0
	v_mov_b32_e32 v56, v0
	v_mov_b32_e32 v57, v0
	v_mov_b32_e32 v58, v0
	v_mov_b32_e32 v59, v0
	v_mov_b32_e32 v60, v0
	v_mov_b32_e32 v61, v0
	v_mov_b32_e32 v62, v0
	v_mov_b32_e32 v63, v0
	v_mov_b32_e32 v80, v0
	v_mov_b32_e32 v81, v0
	v_mov_b32_e32 v82, v0
	v_mov_b32_e32 v83, v0
	v_mov_b32_e32 v84, v0
	v_mov_b32_e32 v85, v0
	v_mov_b32_e32 v86, v0
	v_mov_b32_e32 v87, v0
	v_mov_b32_e32 v96, v0
	v_mov_b32_e32 v97, v0
	v_mov_b32_e32 v98, v0
	v_mov_b32_e32 v99, v0
	v_mov_b32_e32 v100, v0
	v_mov_b32_e32 v101, v0
	v_mov_b32_e32 v102, v0
	v_mov_b32_e32 v103, v0
	v_mov_b32_e32 v112, v0
	v_mov_b32_e32 v113, v0
	v_mov_b32_e32 v114, v0
	v_mov_b32_e32 v115, v0
	v_mov_b32_e32 v116, v0
	v_mov_b32_e32 v117, v0
	v_mov_b32_e32 v118, v0
	v_mov_b32_e32 v119, v0
	v_mov_b32_e32 v128, v0
	v_mov_b32_e32 v129, v0
	v_mov_b32_e32 v130, v0
	v_mov_b32_e32 v131, v0
	v_mov_b32_e32 v132, v0
	v_mov_b32_e32 v133, v0
	v_mov_b32_e32 v134, v0
	v_mov_b32_e32 v135, v0
	v_mov_b32_e32 v88, v0
	v_mov_b32_e32 v89, v0
	v_mov_b32_e32 v90, v0
	v_mov_b32_e32 v91, v0
	v_mov_b32_e32 v92, v0
	v_mov_b32_e32 v93, v0
	v_mov_b32_e32 v94, v0
	v_mov_b32_e32 v95, v0
	v_mov_b32_e32 v104, v0
	v_mov_b32_e32 v105, v0
	v_mov_b32_e32 v106, v0
	v_mov_b32_e32 v107, v0
	v_mov_b32_e32 v108, v0
	v_mov_b32_e32 v109, v0
	v_mov_b32_e32 v110, v0
	v_mov_b32_e32 v111, v0
	v_mov_b32_e32 v120, v0
	v_mov_b32_e32 v121, v0
	v_mov_b32_e32 v122, v0
	v_mov_b32_e32 v123, v0
	v_mov_b32_e32 v124, v0
	v_mov_b32_e32 v125, v0
	v_mov_b32_e32 v126, v0
	v_mov_b32_e32 v127, v0
	v_mov_b32_e32 v136, v0
	v_mov_b32_e32 v137, v0
	v_mov_b32_e32 v138, v0
	v_mov_b32_e32 v139, v0
	v_mov_b32_e32 v140, v0
	v_mov_b32_e32 v141, v0
	v_mov_b32_e32 v142, v0
	v_mov_b32_e32 v143, v0
